# v122 stack plus GEMM first-unit prologue de-serialisation: K-tile 1 LDS-DMA issued before the wait+barrier that retires K-tile 0 (all 7 GEMM copies)
# baseline (speedup 1.0000x reference)
.LBB0_38:
	v_lshrrev_b32_e32 v16, 1, v0
	v_mov_b32_e32 v133, v177
	v_and_b32_e32 v16, 24, v16
	v_lshl_add_u64 v[8:9], s[46:47], 0, v[132:133]
	v_mov_b32_e32 v129, v177
	v_and_b32_e32 v7, 15, v0
	v_lshlrev_b32_e32 v17, 1, v16
	v_lshlrev_b32_e32 v0, 2, v0
	s_lshl_b32 s1, s1, 5
	v_lshl_add_u64 v[10:11], s[46:47], 0, v[128:129]
	v_mov_b32_e32 v135, v177
	s_lshl_b32 s20, s0, 6
	v_lshl_or_b32 v17, v7, 6, v17
	v_and_b32_e32 v0, 32, v0
	s_lshl_b32 s0, s0, 13
	s_and_b32 s21, s1, 0x60
	s_add_i32 m0, s66, 0x18000
	v_lshl_add_u64 v[8:9], v[8:9], 0, s[26:27]
	v_lshl_add_u64 v[12:13], s[44:45], 0, v[134:135]
	v_mov_b32_e32 v131, v177
	v_bitop3_b32 v18, v17, s0, v0 bitop3:0xde
	s_lshl_b32 s0, s21, 7
	s_nop 0
	global_load_lds_dwordx4 v[8:9], off
	v_lshl_add_u64 v[8:9], v[10:11], 0, s[26:27]
	s_add_i32 m0, s66, 0x1a000
	s_add_i32 s48, s66, 0x8000
	s_add_i32 s49, s66, 0xa000
	v_lshl_add_u64 v[14:15], s[44:45], 0, v[130:131]
	v_bitop3_b32 v142, v17, s0, v0 bitop3:0xde
	global_load_lds_dwordx4 v[8:9], off
	v_lshl_add_u64 v[8:9], v[12:13], 0, s[26:27]
	s_mov_b32 m0, s48
	s_add_u32 s0, s46, 0x10080
	global_load_lds_dwordx4 v[8:9], off
	v_lshl_add_u64 v[8:9], v[14:15], 0, s[26:27]
	s_mov_b32 m0, s49
	s_addc_u32 s1, s47, 0
	global_load_lds_dwordx4 v[8:9], off
	s_add_i32 m0, s66, 0x1c000
	v_lshl_add_u64 v[8:9], s[0:1], 0, v[132:133]
	global_load_lds_dwordx4 v[8:9], off
	v_lshl_add_u64 v[8:9], s[0:1], 0, v[128:129]
	s_add_i32 m0, s66, 0x1e000
	v_lshlrev_b32_e32 v0, 14, v1
	global_load_lds_dwordx4 v[8:9], off
	s_waitcnt vmcnt(8)
	s_barrier
	v_and_b32_e32 v0, 0xffff8000, v0
	v_lshl_add_u32 v0, v2, 11, v0
	v_and_b32_e32 v1, 1, v1
	v_lshl_or_b32 v0, v1, 6, v0
	s_cmpk_lt_u32 s30, 0x100
	v_lshl_add_u32 v138, v3, 1, v0
	v_lshlrev_b32_e32 v0, 14, v4
	s_cselect_b64 s[0:1], -1, 0
	v_and_b32_e32 v0, 0xffff8000, v0
	s_waitcnt vmcnt(6)
	v_writelane_b32 v252, s0, 28
	v_lshl_add_u32 v0, v5, 11, v0
	v_and_b32_e32 v1, 1, v4
	v_writelane_b32 v252, s1, 29
	s_ashr_i32 s0, s20, 31
	v_lshl_or_b32 v0, v1, 6, v0
	v_or_b32_e32 v136, s20, v7
	v_mov_b32_e32 v137, s0
	v_mov_b32_e32 v139, v177
	v_lshl_add_u32 v140, v6, 1, v0
	v_mov_b32_e32 v141, v177
	s_mov_b32 s50, 0
	v_add_u32_e32 v143, 0, v18
	s_lshl_b32 s70, s21, 1
	v_lshlrev_b32_e32 v176, 1, v16
	s_barrier
	s_branch .LBB0_41

.LBB0_96:
	s_and_b32 s0, s21, 3
	s_add_i32 m0, s66, 0x18000
	v_lshl_add_u64 v[4:5], v[4:5], 0, s[26:27]
	s_lshl_b32 s21, s20, 13
	s_lshl_b32 s37, s0, 12
	s_nop 0
	global_load_lds_dwordx4 v[4:5], off
	v_lshl_add_u64 v[2:3], v[2:3], 0, s[26:27]
	s_add_i32 m0, s66, 0x1a000
	s_add_i32 s48, s66, 0x8000
	s_add_i32 s49, s66, 0xa000
	global_load_lds_dwordx4 v[2:3], off
	v_lshl_add_u64 v[0:1], v[0:1], 0, s[26:27]
	s_mov_b32 m0, s48
	s_add_u32 s50, s46, 0x10080
	global_load_lds_dwordx4 v[0:1], off
	v_lshl_add_u64 v[0:1], v[6:7], 0, s[26:27]
	s_mov_b32 m0, s49
	s_addc_u32 s51, s47, 0
	global_load_lds_dwordx4 v[0:1], off
	s_add_i32 m0, s66, 0x1c000
	v_lshl_add_u64 v[0:1], s[50:51], 0, v[140:141]
	global_load_lds_dwordx4 v[0:1], off
	v_lshl_add_u64 v[0:1], s[50:51], 0, v[136:137]
	s_add_i32 m0, s66, 0x1e000
	v_lshrrev_b32_e32 v2, 1, v8
	global_load_lds_dwordx4 v[0:1], off
	s_waitcnt vmcnt(8)
	s_barrier
	v_and_b32_e32 v1, 15, v8
	v_and_b32_e32 v2, 24, v2
	v_lshl_or_b32 v0, s20, 6, v1
	v_lshlrev_b32_e32 v3, 2, v8
	v_lshlrev_b32_e32 v4, 1, v2
	v_and_b32_e32 v3, 32, v3
	v_lshl_or_b32 v1, v1, 6, v4
	v_or_b32_e32 v4, 16, v0
	v_bitop3_b32 v6, v1, s21, v3 bitop3:0xde
	v_bitop3_b32 v180, v1, s37, v3 bitop3:0xde
	v_ashrrev_i32_e32 v1, 31, v0
	v_ashrrev_i32_e32 v5, 31, v4
	v_lshlrev_b64 v[144:145], 12, v[0:1]
	v_lshlrev_b64 v[148:149], 12, v[4:5]
	v_or_b32_e32 v4, 32, v0
	v_or_b32_e32 v0, 48, v0
	s_cmpk_lt_u32 s30, 0x100
	v_readlane_b32 s20, v253, 6
	v_ashrrev_i32_e32 v1, 31, v0
	s_cselect_b64 s[4:5], -1, 0
	s_add_i32 s20, s20, 9
	v_lshlrev_b64 v[152:153], 12, v[0:1]
	v_lshlrev_b32_e32 v0, 14, v9
	v_writelane_b32 v252, s4, 28
	s_cmp_lt_u32 s20, 21
	v_and_b32_e32 v0, 0xffff8000, v0
	v_writelane_b32 v252, s5, 29
	s_cselect_b64 s[4:5], -1, 0
	v_lshl_add_u32 v0, v10, 11, v0
	v_and_b32_e32 v1, 1, v9
	v_writelane_b32 v252, s4, 26
	v_lshl_or_b32 v0, v1, 6, v0
	v_lshl_add_u32 v160, v11, 1, v0
	v_writelane_b32 v252, s5, 27
	s_mov_b64 s[4:5], 0x80000
	v_lshlrev_b32_e32 v0, 14, v12
	v_lshl_add_u64 v[146:147], v[144:145], 0, s[4:5]
	s_mov_b64 s[4:5], 0x90000
	v_and_b32_e32 v0, 0xffff8000, v0
	s_waitcnt vmcnt(6)
	v_lshl_add_u64 v[154:155], v[144:145], 0, s[4:5]
	s_mov_b64 s[4:5], 0xa0000
	v_lshl_add_u32 v0, v13, 11, v0
	v_and_b32_e32 v1, 1, v12
	v_lshl_or_b32 v2, s0, 6, v2
	v_ashrrev_i32_e32 v5, 31, v4
	v_lshl_add_u64 v[156:157], v[144:145], 0, s[4:5]
	s_mov_b64 s[4:5], 0xb0000
	v_lshl_or_b32 v0, v1, 6, v0
	v_lshlrev_b64 v[150:151], 12, v[4:5]
	v_lshl_add_u64 v[158:159], v[144:145], 0, s[4:5]
	v_mov_b32_e32 v161, v177
	v_lshl_add_u32 v162, v14, 1, v0
	v_mov_b32_e32 v163, v177
	s_mov_b32 s50, 0
	v_add_u32_e32 v181, 0, v6
	v_lshlrev_b32_e32 v176, 2, v2
	s_barrier
	v_readlane_b32 s21, v253, 7
	s_branch .LBB0_99

.LBB0_142:
	v_lshrrev_b32_e32 v16, 1, v0
	v_and_b32_e32 v16, 24, v16
	v_lshl_add_u64 v[8:9], s[56:57], 0, v[176:177]
	v_mov_b32_e32 v167, v177
	v_and_b32_e32 v7, 15, v0
	v_lshlrev_b32_e32 v17, 1, v16
	v_lshlrev_b32_e32 v0, 2, v0
	v_lshl_add_u64 v[10:11], s[56:57], 0, v[166:167]
	v_mov_b32_e32 v163, v177
	s_and_b32 s37, s20, 3
	v_lshl_or_b32 v17, v7, 6, v17
	s_lshl_b32 s20, s21, 13
	v_and_b32_e32 v0, 32, v0
	s_add_i32 m0, s35, 0x18000
	v_lshl_add_u64 v[8:9], v[8:9], 0, s[26:27]
	v_lshl_add_u64 v[12:13], s[54:55], 0, v[162:163]
	v_mov_b32_e32 v165, v177
	s_lshl_b32 s39, s21, 6
	v_bitop3_b32 v18, v17, s20, v0 bitop3:0xde
	s_lshl_b32 s20, s37, 12
	s_nop 0
	global_load_lds_dwordx4 v[8:9], off
	v_lshl_add_u64 v[8:9], v[10:11], 0, s[26:27]
	s_add_i32 m0, s35, 0x1a000
	s_add_i32 s65, s35, 0x8000
	s_add_i32 s66, s35, 0xa000
	v_lshl_add_u64 v[14:15], s[54:55], 0, v[164:165]
	v_bitop3_b32 v207, v17, s20, v0 bitop3:0xde
	global_load_lds_dwordx4 v[8:9], off
	v_lshl_add_u64 v[8:9], v[12:13], 0, s[26:27]
	s_mov_b32 m0, s65
	s_add_u32 s20, s56, 0x20080
	global_load_lds_dwordx4 v[8:9], off
	v_lshl_add_u64 v[8:9], v[14:15], 0, s[26:27]
	s_mov_b32 m0, s66
	s_addc_u32 s21, s57, 0
	global_load_lds_dwordx4 v[8:9], off
	s_add_i32 m0, s35, 0x1c000
	v_lshl_add_u64 v[8:9], s[20:21], 0, v[176:177]
	global_load_lds_dwordx4 v[8:9], off
	v_lshl_add_u64 v[8:9], s[20:21], 0, v[166:167]
	s_add_i32 m0, s35, 0x1e000
	v_lshlrev_b32_e32 v0, 15, v1
	global_load_lds_dwordx4 v[8:9], off
	s_waitcnt vmcnt(8)
	s_barrier
	v_and_b32_e32 v0, 0xffff0000, v0
	v_lshl_add_u32 v0, v2, 12, v0
	v_and_b32_e32 v1, 1, v1
	v_lshl_or_b32 v0, v1, 6, v0
	s_cmpk_lt_u32 s30, 0x100
	v_lshl_add_u32 v178, v3, 1, v0
	v_lshlrev_b32_e32 v0, 15, v4
	s_cselect_b64 s[48:49], -1, 0
	s_ashr_i32 s20, s39, 31
	v_and_b32_e32 v0, 0xffff0000, v0
	s_waitcnt vmcnt(6)
	v_or_b32_e32 v168, s39, v7
	v_mov_b32_e32 v169, s20
	v_lshl_add_u32 v0, v5, 12, v0
	v_and_b32_e32 v1, 1, v4
	v_lshl_add_u64 v[172:173], v[168:169], 0, s[26:27]
	v_lshl_or_b32 v0, v1, 6, v0
	v_lshlrev_b64 v[170:171], 11, v[168:169]
	v_lshlrev_b64 v[174:175], 11, v[172:173]
	s_lshl_b32 s67, s22, 2
	s_lshr_b32 s68, s22, 3
	v_lshl_or_b32 v208, s37, 6, v16
	v_mov_b32_e32 v179, v177
	v_lshl_add_u32 v180, v6, 1, v0
	v_mov_b32_e32 v181, v177
	s_mov_b32 s22, 0
	v_add_u32_e32 v209, 0, v18
	s_mov_b32 s70, 0
	s_barrier
	s_branch .LBB0_145

.LBB0_620:
	s_and_b32 s22, s20, 3
	s_add_i32 m0, s56, 0x18000
	v_lshl_add_u64 v[4:5], v[4:5], 0, s[26:27]
	s_lshl_b32 s4, s1, 6
	s_lshl_b32 s1, s1, 13
	s_lshl_b32 s30, s22, 12
	s_nop 0
	global_load_lds_dwordx4 v[4:5], off
	v_lshl_add_u64 v[2:3], v[2:3], 0, s[26:27]
	s_add_i32 m0, s56, 0x1a000
	s_add_i32 s34, s56, 0x8000
	s_add_i32 s53, s56, 0xa000
	global_load_lds_dwordx4 v[2:3], off
	v_lshl_add_u64 v[0:1], v[0:1], 0, s[26:27]
	s_mov_b32 m0, s34
	s_add_u32 s20, s50, 0x10080
	global_load_lds_dwordx4 v[0:1], off
	v_lshl_add_u64 v[0:1], v[6:7], 0, s[26:27]
	s_mov_b32 m0, s53
	s_addc_u32 s21, s51, 0
	global_load_lds_dwordx4 v[0:1], off
	s_add_i32 m0, s56, 0x1c000
	v_lshl_add_u64 v[0:1], s[20:21], 0, v[132:133]
	global_load_lds_dwordx4 v[0:1], off
	v_lshl_add_u64 v[0:1], s[20:21], 0, v[128:129]
	s_add_i32 m0, s56, 0x1e000
	v_bfe_u32 v161, v8, 4, 2
	global_load_lds_dwordx4 v[0:1], off
	s_waitcnt vmcnt(8)
	s_barrier
	v_and_b32_e32 v160, 15, v8
	v_lshlrev_b32_e32 v0, 2, v8
	v_lshlrev_b32_e32 v1, 4, v161
	v_and_b32_e32 v0, 32, v0
	v_lshl_or_b32 v1, v160, 6, v1
	s_cmpk_lt_u32 s0, 0x100
	v_bitop3_b32 v2, v1, s1, v0 bitop3:0xde
	s_cselect_b64 s[0:1], -1, 0
	v_bitop3_b32 v162, v1, s30, v0 bitop3:0xde
	v_writelane_b32 v252, s0, 26
	v_lshlrev_b32_e32 v0, 14, v9
	v_and_b32_e32 v0, 0xffff8000, v0
	v_writelane_b32 v252, s1, 27
	s_lshl_b32 s0, s22, 6
	v_writelane_b32 v252, s0, 28
	s_add_i32 s0, s4, 0x80
	v_lshl_add_u32 v0, v10, 11, v0
	v_and_b32_e32 v1, 1, v9
	v_writelane_b32 v252, s0, 30
	v_lshl_or_b32 v0, v1, 6, v0
	v_readlane_b32 s0, v252, 19
	v_lshl_add_u32 v140, v11, 1, v0
	v_lshlrev_b32_e32 v0, 14, v12
	v_readlane_b32 s1, v252, 20
	s_lshl_b32 s0, s0, 7
	v_and_b32_e32 v0, 0xffff8000, v0
	s_waitcnt vmcnt(6)
	s_ashr_i32 s1, s0, 31
	v_lshl_add_u32 v0, v13, 11, v0
	v_and_b32_e32 v1, 1, v12
	s_ashr_i32 s20, s4, 31
	v_writelane_b32 v252, s4, 32
	v_lshl_or_b32 v0, v1, 6, v0
	s_lshl_b64 s[0:1], s[0:1], 2
	v_lshlrev_b32_e32 v136, 3, v161
	v_or_b32_e32 v163, 16, v160
	v_or_b32_e32 v164, 32, v160
	v_or_b32_e32 v165, 48, v160
	v_bitop3_b32 v166, s4, v204, v160 bitop3:0xc8
	v_or_b32_e32 v138, s4, v160
	v_mov_b32_e32 v139, s20
	v_and_or_b32 v167, s4, 64, v160
	v_mov_b32_e32 v141, v177
	v_lshl_add_u32 v142, v14, 1, v0
	v_mov_b32_e32 v143, v177
	s_mov_b32 s35, 0
	v_add_u32_e32 v168, 0, v2
	v_writelane_b32 v252, s0, 34
	s_barrier
	s_nop 0
	v_writelane_b32 v252, s1, 35
	s_branch .LBB0_623

.LBB0_1155:
	s_and_b32 s22, s20, 3
	s_add_i32 m0, s56, 0x18000
	v_lshl_add_u64 v[4:5], v[4:5], 0, s[26:27]
	s_lshl_b32 s4, s1, 6
	s_lshl_b32 s1, s1, 13
	s_lshl_b32 s30, s22, 12
	s_nop 0
	global_load_lds_dwordx4 v[4:5], off
	v_lshl_add_u64 v[2:3], v[2:3], 0, s[26:27]
	s_add_i32 m0, s56, 0x1a000
	s_add_i32 s35, s56, 0x8000
	s_add_i32 s53, s56, 0xa000
	global_load_lds_dwordx4 v[2:3], off
	v_lshl_add_u64 v[0:1], v[0:1], 0, s[26:27]
	s_mov_b32 m0, s35
	s_add_u32 s20, s50, 0x10080
	global_load_lds_dwordx4 v[0:1], off
	v_lshl_add_u64 v[0:1], v[6:7], 0, s[26:27]
	s_mov_b32 m0, s53
	s_addc_u32 s21, s51, 0
	global_load_lds_dwordx4 v[0:1], off
	s_add_i32 m0, s56, 0x1c000
	v_lshl_add_u64 v[0:1], s[20:21], 0, v[132:133]
	global_load_lds_dwordx4 v[0:1], off
	v_lshl_add_u64 v[0:1], s[20:21], 0, v[128:129]
	s_add_i32 m0, s56, 0x1e000
	v_bfe_u32 v161, v8, 4, 2
	global_load_lds_dwordx4 v[0:1], off
	s_waitcnt vmcnt(8)
	s_barrier
	v_and_b32_e32 v160, 15, v8
	v_lshlrev_b32_e32 v0, 2, v8
	v_lshlrev_b32_e32 v1, 4, v161
	v_and_b32_e32 v0, 32, v0
	v_lshl_or_b32 v1, v160, 6, v1
	s_cmpk_lt_u32 s0, 0x100
	v_bitop3_b32 v2, v1, s1, v0 bitop3:0xde
	s_cselect_b64 s[0:1], -1, 0
	v_bitop3_b32 v162, v1, s30, v0 bitop3:0xde
	v_writelane_b32 v252, s0, 26
	v_lshlrev_b32_e32 v0, 14, v9
	v_and_b32_e32 v0, 0xffff8000, v0
	v_writelane_b32 v252, s1, 27
	s_lshl_b32 s0, s22, 6
	v_writelane_b32 v252, s0, 28
	s_add_i32 s0, s4, 0x80
	v_lshl_add_u32 v0, v10, 11, v0
	v_and_b32_e32 v1, 1, v9
	v_writelane_b32 v252, s0, 30
	v_lshl_or_b32 v0, v1, 6, v0
	v_readlane_b32 s0, v252, 19
	v_lshl_add_u32 v140, v11, 1, v0
	v_lshlrev_b32_e32 v0, 14, v12
	v_readlane_b32 s1, v252, 20
	s_lshl_b32 s0, s0, 7
	v_and_b32_e32 v0, 0xffff8000, v0
	s_waitcnt vmcnt(6)
	s_ashr_i32 s1, s0, 31
	v_lshl_add_u32 v0, v13, 11, v0
	v_and_b32_e32 v1, 1, v12
	s_ashr_i32 s20, s4, 31
	v_writelane_b32 v252, s4, 32
	v_lshl_or_b32 v0, v1, 6, v0
	s_lshl_b64 s[0:1], s[0:1], 2
	v_lshlrev_b32_e32 v136, 3, v161
	v_or_b32_e32 v163, 16, v160
	v_or_b32_e32 v164, 32, v160
	v_or_b32_e32 v165, 48, v160
	v_bitop3_b32 v166, s4, v204, v160 bitop3:0xc8
	v_or_b32_e32 v138, s4, v160
	v_mov_b32_e32 v139, s20
	v_and_or_b32 v167, s4, 64, v160
	v_mov_b32_e32 v141, v177
	v_lshl_add_u32 v142, v14, 1, v0
	v_mov_b32_e32 v143, v177
	s_mov_b32 s34, 0
	v_add_u32_e32 v168, 0, v2
	v_writelane_b32 v252, s0, 34
	s_barrier
	s_nop 0
	v_writelane_b32 v252, s1, 35
	s_branch .LBB0_1158

.LBB0_1231:
	v_lshrrev_b32_e32 v19, 1, v8
	v_and_b32_e32 v19, 24, v19
	v_and_b32_e32 v17, 15, v8
	v_lshlrev_b32_e32 v8, 2, v8
	v_lshlrev_b32_e32 v20, 1, v19
	v_lshl_or_b32 v18, s20, 6, v17
	v_and_b32_e32 v8, 32, v8
	s_and_b32 s37, s21, 3
	v_lshl_or_b32 v17, v17, 6, v20
	s_lshl_b32 s20, s20, 13
	s_add_i32 m0, s62, 0x18000
	v_lshl_add_u64 v[6:7], v[6:7], 0, s[26:27]
	v_bitop3_b32 v20, v17, s20, v8 bitop3:0xde
	s_lshl_b32 s20, s37, 12
	s_nop 0
	global_load_lds_dwordx4 v[6:7], off
	v_lshl_add_u64 v[4:5], v[4:5], 0, s[26:27]
	s_add_i32 m0, s62, 0x1a000
	s_add_i32 s66, s62, 0x8000
	s_add_i32 s67, s62, 0xa000
	v_bitop3_b32 v178, v17, s20, v8 bitop3:0xde
	global_load_lds_dwordx4 v[4:5], off
	v_lshl_add_u64 v[0:1], v[0:1], 0, s[26:27]
	s_mov_b32 m0, s66
	s_add_u32 s20, s46, 0x2c080
	global_load_lds_dwordx4 v[0:1], off
	v_lshl_add_u64 v[0:1], v[2:3], 0, s[26:27]
	s_mov_b32 m0, s67
	s_addc_u32 s21, s47, 0
	global_load_lds_dwordx4 v[0:1], off
	s_add_i32 m0, s62, 0x1c000
	v_lshl_add_u64 v[0:1], s[20:21], 0, v[140:141]
	global_load_lds_dwordx4 v[0:1], off
	v_lshl_add_u64 v[0:1], s[20:21], 0, v[136:137]
	s_add_i32 m0, s62, 0x1e000
	s_cmpk_lt_u32 s34, 0x100
	global_load_lds_dwordx4 v[0:1], off
	s_waitcnt vmcnt(8)
	s_barrier
	s_cselect_b64 s[4:5], -1, 0
	v_writelane_b32 v252, s4, 28
	v_lshl_or_b32 v0, s37, 6, v19
	v_ashrrev_i32_e32 v19, 31, v18
	v_or_b32_e32 v2, 16, v18
	v_writelane_b32 v252, s5, 29
	v_lshlrev_b64 v[144:145], 12, v[18:19]
	s_mov_b64 s[4:5], 0x80000
	v_ashrrev_i32_e32 v3, 31, v2
	v_lshl_add_u64 v[146:147], v[144:145], 0, s[4:5]
	v_lshlrev_b64 v[148:149], 12, v[2:3]
	v_or_b32_e32 v2, 32, v18
	s_mov_b64 s[4:5], 0x90000
	v_ashrrev_i32_e32 v3, 31, v2
	v_lshl_add_u64 v[154:155], v[144:145], 0, s[4:5]
	s_mov_b64 s[4:5], 0xa0000
	v_lshlrev_b64 v[150:151], 12, v[2:3]
	v_or_b32_e32 v2, 48, v18
	v_lshl_add_u64 v[156:157], v[144:145], 0, s[4:5]
	s_mov_b64 s[4:5], 0xb0000
	v_ashrrev_i32_e32 v3, 31, v2
	v_lshl_add_u64 v[158:159], v[144:145], 0, s[4:5]
	s_movk_i32 s4, 0xb00
	v_lshlrev_b64 v[152:153], 12, v[2:3]
	v_lshrrev_b32_e32 v1, 1, v9
	v_mul_lo_u32 v2, v10, s4
	s_mov_b32 s5, 0xb000
	v_mad_u64_u32 v[2:3], s[20:21], v1, s5, v[2:3]
	v_or_b32_e32 v1, v2, v16
	v_add_lshl_u32 v176, v1, v15, 1
	v_lshrrev_b32_e32 v1, 1, v11
	v_mul_lo_u32 v2, v12, s4
	v_mad_u64_u32 v[2:3], s[20:21], v1, s5, v[2:3]
	s_waitcnt vmcnt(6)
	s_mov_b64 s[6:7], 0xb0080
	v_or_b32_e32 v1, v2, v14
	v_lshl_add_u64 v[160:161], v[176:177], 0, s[6:7]
	v_add_lshl_u32 v176, v1, v13, 1
	s_movk_i32 s91, 0xb00
	v_lshl_add_u64 v[162:163], v[176:177], 0, s[6:7]
	s_mov_b32 s68, 0
	v_add_u32_e32 v179, 0, v20
	v_lshlrev_b32_e32 v176, 2, v0
	s_barrier
	s_branch .LBB0_1234
